# attention: cross-half row max via v_permlane32_swap instead of ds_bpermute (on top of lazy rescale)
# baseline (speedup 1.0000x reference)
.LBB0_1738:
	s_nop 4
	v_max3_f32 v183, v80, v81, v82
	v_max3_f32 v184, v88, v89, v90
	v_max3_f32 v183, v183, v83, v84
	v_max3_f32 v184, v184, v91, v92
	v_max3_f32 v183, v183, v85, v86
	v_max3_f32 v184, v184, v93, v94
	v_max_f32_e32 v183, v183, v87
	v_max_f32_e32 v184, v184, v95
	v_max3_f32 v181, v64, v65, v66
	v_max3_f32 v182, v72, v73, v74
	v_max3_f32 v181, v181, v67, v68
	v_max3_f32 v182, v182, v75, v76
	v_max3_f32 v181, v181, v69, v70
	v_max3_f32 v182, v182, v77, v78
	v_max_f32_e32 v181, v181, v71
	v_max_f32_e32 v182, v182, v79
	v_max3_f32 v181, v181, v182, v183
	v_max_f32_e32 v181, v181, v184
	s_or_b64 s[0:1], s[8:9], s[0:1]
	v_cndmask_b32_e64 v181, v159, v181, s[0:1]
	v_mov_b32_e32 v182, v181
	s_nop 1
	v_permlane32_swap_b32_e32 v181, v182
	v_max3_f32 v181, v154, v181, v182
	v_sub_f32_e32 v182, v181, v154
	v_cmp_lt_f32_e32 vcc, 0x41000000, v182
	s_nop 1
	v_cndmask_b32_e32 v181, v154, v181, vcc
	v_sub_f32_e32 v154, v154, v181
	v_exp_f32_e32 v154, v154
	s_nop 0
	v_cmp_neq_f32_e32 vcc, 1.0, v154
	s_cbranch_vccz .LBB0_1727
	v_pk_mul_f32 v[62:63], v[62:63], v[154:155] op_sel_hi:[1,0]
	v_pk_mul_f32 v[60:61], v[60:61], v[154:155] op_sel_hi:[1,0]
	v_pk_mul_f32 v[58:59], v[58:59], v[154:155] op_sel_hi:[1,0]
	v_pk_mul_f32 v[56:57], v[56:57], v[154:155] op_sel_hi:[1,0]
	v_pk_mul_f32 v[54:55], v[54:55], v[154:155] op_sel_hi:[1,0]
	v_pk_mul_f32 v[52:53], v[52:53], v[154:155] op_sel_hi:[1,0]
	v_pk_mul_f32 v[50:51], v[50:51], v[154:155] op_sel_hi:[1,0]
	v_pk_mul_f32 v[48:49], v[48:49], v[154:155] op_sel_hi:[1,0]
	v_pk_mul_f32 v[46:47], v[46:47], v[154:155] op_sel_hi:[1,0]
	v_pk_mul_f32 v[44:45], v[44:45], v[154:155] op_sel_hi:[1,0]
	v_pk_mul_f32 v[42:43], v[42:43], v[154:155] op_sel_hi:[1,0]
	v_pk_mul_f32 v[40:41], v[40:41], v[154:155] op_sel_hi:[1,0]
	v_pk_mul_f32 v[38:39], v[38:39], v[154:155] op_sel_hi:[1,0]
	v_pk_mul_f32 v[36:37], v[36:37], v[154:155] op_sel_hi:[1,0]
	v_pk_mul_f32 v[34:35], v[34:35], v[154:155] op_sel_hi:[1,0]
	v_pk_mul_f32 v[32:33], v[32:33], v[154:155] op_sel_hi:[1,0]
	v_pk_mul_f32 v[30:31], v[30:31], v[154:155] op_sel_hi:[1,0]
	v_pk_mul_f32 v[28:29], v[28:29], v[154:155] op_sel_hi:[1,0]
	v_pk_mul_f32 v[26:27], v[26:27], v[154:155] op_sel_hi:[1,0]
	v_pk_mul_f32 v[24:25], v[24:25], v[154:155] op_sel_hi:[1,0]
	v_pk_mul_f32 v[22:23], v[22:23], v[154:155] op_sel_hi:[1,0]
	v_pk_mul_f32 v[20:21], v[20:21], v[154:155] op_sel_hi:[1,0]
	v_pk_mul_f32 v[18:19], v[18:19], v[154:155] op_sel_hi:[1,0]
	v_pk_mul_f32 v[16:17], v[16:17], v[154:155] op_sel_hi:[1,0]
	v_pk_mul_f32 v[14:15], v[14:15], v[154:155] op_sel_hi:[1,0]
	v_pk_mul_f32 v[12:13], v[12:13], v[154:155] op_sel_hi:[1,0]
	v_pk_mul_f32 v[10:11], v[10:11], v[154:155] op_sel_hi:[1,0]
	v_pk_mul_f32 v[8:9], v[8:9], v[154:155] op_sel_hi:[1,0]
	v_pk_mul_f32 v[6:7], v[6:7], v[154:155] op_sel_hi:[1,0]
	v_pk_mul_f32 v[4:5], v[4:5], v[154:155] op_sel_hi:[1,0]
	v_pk_mul_f32 v[2:3], v[2:3], v[154:155] op_sel_hi:[1,0]
	v_pk_mul_f32 v[0:1], v[0:1], v[154:155] op_sel_hi:[1,0]
	s_branch .LBB0_1727

.LBB0_1749:
	s_nop 4
	v_max3_f32 v98, v80, v81, v82
	v_max3_f32 v99, v88, v89, v90
	v_max3_f32 v98, v98, v83, v84
	v_max3_f32 v99, v99, v91, v92
	v_max3_f32 v98, v98, v85, v86
	v_max3_f32 v99, v99, v93, v94
	v_max_f32_e32 v98, v98, v87
	v_max_f32_e32 v99, v99, v95
	v_max3_f32 v96, v64, v65, v66
	v_max3_f32 v97, v72, v73, v74
	v_max3_f32 v96, v96, v67, v68
	v_max3_f32 v97, v97, v75, v76
	v_max3_f32 v96, v96, v69, v70
	v_max3_f32 v97, v97, v77, v78
	v_max_f32_e32 v96, v96, v71
	v_max_f32_e32 v97, v97, v79
	v_max3_f32 v96, v96, v97, v98
	v_max_f32_e32 v96, v96, v99
	s_or_b64 s[0:1], s[8:9], s[0:1]
	v_cndmask_b32_e64 v96, v159, v96, s[0:1]
	v_mov_b32_e32 v97, v96
	s_nop 1
	v_permlane32_swap_b32_e32 v96, v97
	v_max3_f32 v97, v154, v96, v97
	v_sub_f32_e32 v96, v97, v154
	v_cmp_lt_f32_e32 vcc, 0x41000000, v96
	s_nop 1
	v_cndmask_b32_e32 v97, v154, v97, vcc
	v_sub_f32_e32 v96, v154, v97
	v_exp_f32_e32 v96, v96
	s_nop 0
	v_cmp_neq_f32_e32 vcc, 1.0, v96
	s_cbranch_vccz .LBB0_1751
	v_pk_mul_f32 v[62:63], v[62:63], v[96:97] op_sel_hi:[1,0]
	v_pk_mul_f32 v[60:61], v[60:61], v[96:97] op_sel_hi:[1,0]
	v_pk_mul_f32 v[58:59], v[58:59], v[96:97] op_sel_hi:[1,0]
	v_pk_mul_f32 v[56:57], v[56:57], v[96:97] op_sel_hi:[1,0]
	v_pk_mul_f32 v[54:55], v[54:55], v[96:97] op_sel_hi:[1,0]
	v_pk_mul_f32 v[52:53], v[52:53], v[96:97] op_sel_hi:[1,0]
	v_pk_mul_f32 v[50:51], v[50:51], v[96:97] op_sel_hi:[1,0]
	v_pk_mul_f32 v[48:49], v[48:49], v[96:97] op_sel_hi:[1,0]
	v_pk_mul_f32 v[46:47], v[46:47], v[96:97] op_sel_hi:[1,0]
	v_pk_mul_f32 v[44:45], v[44:45], v[96:97] op_sel_hi:[1,0]
	v_pk_mul_f32 v[42:43], v[42:43], v[96:97] op_sel_hi:[1,0]
	v_pk_mul_f32 v[40:41], v[40:41], v[96:97] op_sel_hi:[1,0]
	v_pk_mul_f32 v[38:39], v[38:39], v[96:97] op_sel_hi:[1,0]
	v_pk_mul_f32 v[36:37], v[36:37], v[96:97] op_sel_hi:[1,0]
	v_pk_mul_f32 v[34:35], v[34:35], v[96:97] op_sel_hi:[1,0]
	v_pk_mul_f32 v[32:33], v[32:33], v[96:97] op_sel_hi:[1,0]
	v_pk_mul_f32 v[30:31], v[30:31], v[96:97] op_sel_hi:[1,0]
	v_pk_mul_f32 v[28:29], v[28:29], v[96:97] op_sel_hi:[1,0]
	v_pk_mul_f32 v[26:27], v[26:27], v[96:97] op_sel_hi:[1,0]
	v_pk_mul_f32 v[24:25], v[24:25], v[96:97] op_sel_hi:[1,0]
	v_pk_mul_f32 v[22:23], v[22:23], v[96:97] op_sel_hi:[1,0]
	v_pk_mul_f32 v[20:21], v[20:21], v[96:97] op_sel_hi:[1,0]
	v_pk_mul_f32 v[18:19], v[18:19], v[96:97] op_sel_hi:[1,0]
	v_pk_mul_f32 v[16:17], v[16:17], v[96:97] op_sel_hi:[1,0]
	v_pk_mul_f32 v[14:15], v[14:15], v[96:97] op_sel_hi:[1,0]
	v_pk_mul_f32 v[12:13], v[12:13], v[96:97] op_sel_hi:[1,0]
	v_pk_mul_f32 v[10:11], v[10:11], v[96:97] op_sel_hi:[1,0]
	v_pk_mul_f32 v[8:9], v[8:9], v[96:97] op_sel_hi:[1,0]
	v_pk_mul_f32 v[6:7], v[6:7], v[96:97] op_sel_hi:[1,0]
	v_pk_mul_f32 v[4:5], v[4:5], v[96:97] op_sel_hi:[1,0]
	v_pk_mul_f32 v[2:3], v[2:3], v[96:97] op_sel_hi:[1,0]
	v_pk_mul_f32 v[0:1], v[0:1], v[96:97] op_sel_hi:[1,0]

.LBB0_1792:
	s_nop 4
	v_max3_f32 v98, v80, v81, v82
	v_max3_f32 v99, v88, v89, v90
	v_max3_f32 v98, v98, v83, v84
	v_max3_f32 v99, v99, v91, v92
	v_max3_f32 v98, v98, v85, v86
	v_max3_f32 v99, v99, v93, v94
	v_max_f32_e32 v98, v98, v87
	v_max_f32_e32 v99, v99, v95
	v_max3_f32 v96, v64, v65, v66
	v_max3_f32 v97, v72, v73, v74
	v_max3_f32 v96, v96, v67, v68
	v_max3_f32 v97, v97, v75, v76
	v_max3_f32 v96, v96, v69, v70
	v_max3_f32 v97, v97, v77, v78
	v_max_f32_e32 v96, v96, v71
	v_max_f32_e32 v97, v97, v79
	v_max3_f32 v96, v96, v97, v98
	v_max_f32_e32 v96, v96, v99
	s_or_b64 s[0:1], s[8:9], s[0:1]
	v_cndmask_b32_e64 v96, v159, v96, s[0:1]
	v_mov_b32_e32 v97, v96
	s_nop 1
	v_permlane32_swap_b32_e32 v96, v97
	v_max3_f32 v97, v154, v96, v97
	v_sub_f32_e32 v96, v97, v154
	v_cmp_lt_f32_e32 vcc, 0x41000000, v96
	s_nop 1
	v_cndmask_b32_e32 v97, v154, v97, vcc
	v_sub_f32_e32 v96, v154, v97
	v_exp_f32_e32 v96, v96
	s_nop 0
	v_cmp_neq_f32_e32 vcc, 1.0, v96
	s_cbranch_vccz .LBB0_1710
	v_pk_mul_f32 v[62:63], v[62:63], v[96:97] op_sel_hi:[1,0]
	v_pk_mul_f32 v[60:61], v[60:61], v[96:97] op_sel_hi:[1,0]
	v_pk_mul_f32 v[58:59], v[58:59], v[96:97] op_sel_hi:[1,0]
	v_pk_mul_f32 v[56:57], v[56:57], v[96:97] op_sel_hi:[1,0]
	v_pk_mul_f32 v[54:55], v[54:55], v[96:97] op_sel_hi:[1,0]
	v_pk_mul_f32 v[52:53], v[52:53], v[96:97] op_sel_hi:[1,0]
	v_pk_mul_f32 v[50:51], v[50:51], v[96:97] op_sel_hi:[1,0]
	v_pk_mul_f32 v[48:49], v[48:49], v[96:97] op_sel_hi:[1,0]
	v_pk_mul_f32 v[46:47], v[46:47], v[96:97] op_sel_hi:[1,0]
	v_pk_mul_f32 v[44:45], v[44:45], v[96:97] op_sel_hi:[1,0]
	v_pk_mul_f32 v[42:43], v[42:43], v[96:97] op_sel_hi:[1,0]
	v_pk_mul_f32 v[40:41], v[40:41], v[96:97] op_sel_hi:[1,0]
	v_pk_mul_f32 v[38:39], v[38:39], v[96:97] op_sel_hi:[1,0]
	v_pk_mul_f32 v[36:37], v[36:37], v[96:97] op_sel_hi:[1,0]
	v_pk_mul_f32 v[34:35], v[34:35], v[96:97] op_sel_hi:[1,0]
	v_pk_mul_f32 v[32:33], v[32:33], v[96:97] op_sel_hi:[1,0]
	v_pk_mul_f32 v[30:31], v[30:31], v[96:97] op_sel_hi:[1,0]
	v_pk_mul_f32 v[28:29], v[28:29], v[96:97] op_sel_hi:[1,0]
	v_pk_mul_f32 v[26:27], v[26:27], v[96:97] op_sel_hi:[1,0]
	v_pk_mul_f32 v[24:25], v[24:25], v[96:97] op_sel_hi:[1,0]
	v_pk_mul_f32 v[22:23], v[22:23], v[96:97] op_sel_hi:[1,0]
	v_pk_mul_f32 v[20:21], v[20:21], v[96:97] op_sel_hi:[1,0]
	v_pk_mul_f32 v[18:19], v[18:19], v[96:97] op_sel_hi:[1,0]
	v_pk_mul_f32 v[16:17], v[16:17], v[96:97] op_sel_hi:[1,0]
	v_pk_mul_f32 v[14:15], v[14:15], v[96:97] op_sel_hi:[1,0]
	v_pk_mul_f32 v[12:13], v[12:13], v[96:97] op_sel_hi:[1,0]
	v_pk_mul_f32 v[10:11], v[10:11], v[96:97] op_sel_hi:[1,0]
	v_pk_mul_f32 v[8:9], v[8:9], v[96:97] op_sel_hi:[1,0]
	v_pk_mul_f32 v[6:7], v[6:7], v[96:97] op_sel_hi:[1,0]
	v_pk_mul_f32 v[4:5], v[4:5], v[96:97] op_sel_hi:[1,0]
	v_pk_mul_f32 v[2:3], v[2:3], v[96:97] op_sel_hi:[1,0]
	v_pk_mul_f32 v[0:1], v[0:1], v[96:97] op_sel_hi:[1,0]
	s_branch .LBB0_1710
